# WF1 weight transposition spread over idle CUs in GLU, G2-exit and G3-exit windows (norm2 keeps 28 pct), WF2 in G4 tail, scan2 split
# speedup vs baseline: 1.0183x; 1.0064x over previous
; __device__ __forceinline__ int opaque_tid() { int t = threadIdx.x; asm volatile("" : "+v"(t)); return t; }
; #define PH(b) if ((PHM >> (b)) & 1)
; #define PHASE_BEGIN unsigned char* ws = opaque_ptr(P.ws); const int z = opaque_zero(); (void)ws; (void)z;
; __global__ void __launch_bounds__(512, 2) mega_fwd(Params P) {
;     ...
;         PH(9) { PHASE_BEGIN
;           pg8::DenseOrder S{P5 + C_V, WGLU, LDP, 1024, MP / 256, 4, G, c, 16}; pg8::EpiGlu E{P5, PIN(I_S5BG) + (size_t)l * 1024};
;           pg8::gemm_phase(lds, LDP, 1024, S, E); }
;     ...
;         for (int rep_ = 0; rep_ < ((PROBE_DUP & 32) ? 2 : 1); ++rep_) PH(1) { PHASE_BEGIN
;             const int tid = opaque_tid(), lane = tid & 63, wave = __builtin_amdgcn_readfirstlane(tid >> 6); const int gw = c * 8 + wave, NGW = (G + z) * 8;
;             const float* wf1 = PIN(I_WF1) + (size_t)l * D * 2 * DFF; const float* wf2 = PIN(I_WF2) + (size_t)l * DFF * D;
;             const int n1 = 32 * 44, n2 = 88 * 8;
;             { const int tot4 = (n1 + n2) * 4; const int s0 = (int)((unsigned)(gw * tot4) / (unsigned)NGW), s1 = (int)((unsigned)((gw + 1) * tot4) / (unsigned)NGW);
;             for (int ss = s0; ss < s1; ++ss) {
;                 const int it = ss >> 2, sub = ss & 3;
;                 if (it < n1) transpose_item<1>(wf1, D, 2 * DFF, WF1, it, sub, lane);
;                 else transpose_item<0>(wf2, DFF, D, WF2, it - n1, sub, lane);
;             } }
.LBB0_1020:
	s_or_b64 exec, exec, s[0:1]
	v_mov_b32_e32 v0, v163
	s_waitcnt lgkmcnt(0)
	v_mov_b32_e32 v2, v162
	s_barrier
	v_readlane_b32 s14, v253, 28
	v_readfirstlane_b32 s5, v0
	v_mov_b32_e32 v0, v1
	v_mov_b32_e32 v18, v208
	v_readlane_b32 s15, v253, 29
	v_readfirstlane_b32 s4, v2
	s_andn2_b64 vcc, exec, s[14:15]
	v_readfirstlane_b32 s0, v0
	v_readfirstlane_b32 s16, v18
	s_cbranch_vccnz .LBB0_1040
	s_cmpk_lt_u32 s2, 0x82
	s_cbranch_scc1 .Lglu_go
	v_writelane_b32 v255, s29, 25
	s_nop 1
	v_writelane_b32 v255, s30, 26
	s_nop 1
	v_writelane_b32 v255, s31, 27
	s_nop 1
	v_writelane_b32 v255, s68, 28
	s_nop 1
	v_writelane_b32 v255, s73, 29
	s_nop 1
	v_writelane_b32 v255, s0, 8
	s_nop 1
	v_writelane_b32 v255, s1, 9
	s_nop 1
	v_writelane_b32 v255, s4, 10
	s_nop 1
	v_writelane_b32 v255, s5, 11
	s_nop 1
	v_writelane_b32 v255, s14, 12
	s_nop 1
	v_writelane_b32 v255, s15, 13
	s_nop 1
	v_writelane_b32 v255, s16, 14
	s_nop 1
	v_writelane_b32 v255, s17, 15
	s_nop 1
	v_writelane_b32 v255, s18, 16
	s_nop 1
	v_writelane_b32 v255, s19, 17
	s_nop 1
	v_writelane_b32 v255, s24, 18
	s_nop 1
	v_writelane_b32 v255, s25, 19
	s_nop 1
	v_writelane_b32 v255, s28, 20
	s_nop 1
	v_writelane_b32 v255, s32, 21
	s_nop 1
	v_writelane_b32 v255, s42, 22
	s_nop 1
	v_writelane_b32 v255, s50, 23
	s_nop 1
	v_writelane_b32 v255, s51, 24
	s_nop 1
	s_sub_u32 s100, s2, 0x82
	s_lshl_b32 s100, s100, 9
	s_add_u32 s100, s100, 0x10000
	s_mov_b32 s101, 0xfc00
	s_mov_b32 s4, 0x20800
	v_writelane_b32 v255, s4, 50
	s_nop 1
	s_branch .Lscan2_entry
.Lscan2_ret:
	s_mov_b64 exec, -1
	s_waitcnt vmcnt(0) lgkmcnt(0)
	s_movk_i32 s73, 0x2000
	s_movk_i32 s100, 0x7e
	s_sub_u32 s101, s2, 0x82
	s_lshl_b32 s101, s101, 3
	s_mov_b32 s4, 0x3f0
	v_writelane_b32 v255, s4, 50
	s_nop 1
	s_mov_b32 s4, 0x0
	v_writelane_b32 v255, s4, 51
	s_nop 1
	s_mov_b32 s4, 0x2
	v_writelane_b32 v255, s4, 53
	s_nop 1
	s_branch .Lw2_entry
.Lw2_ret_glu:
	s_mov_b64 exec, -1
	s_waitcnt vmcnt(0) lgkmcnt(0)
	v_readlane_b32 s29, v255, 25
	v_readlane_b32 s30, v255, 26
	v_readlane_b32 s31, v255, 27
	v_readlane_b32 s68, v255, 28
	v_readlane_b32 s73, v255, 29
	v_readlane_b32 s0, v255, 8
	v_readlane_b32 s1, v255, 9
	v_readlane_b32 s4, v255, 10
	v_readlane_b32 s5, v255, 11
	v_readlane_b32 s14, v255, 12
	v_readlane_b32 s15, v255, 13
	v_readlane_b32 s16, v255, 14
	v_readlane_b32 s17, v255, 15
	v_readlane_b32 s18, v255, 16
	v_readlane_b32 s19, v255, 17
	v_readlane_b32 s24, v255, 18
	v_readlane_b32 s25, v255, 19
	v_readlane_b32 s28, v255, 20
	v_readlane_b32 s32, v255, 21
	v_readlane_b32 s42, v255, 22
	v_readlane_b32 s50, v255, 23
	v_readlane_b32 s51, v255, 24
	s_nop 4
	s_branch .LBB0_1040

; #define PH(b) if ((PHM >> (b)) & 1)
; #define PHASE_BEGIN unsigned char* ws = opaque_ptr(P.ws); const int z = opaque_zero(); (void)ws; (void)z;
; #define GSYNC() xcd_barrier(xbar)
; __global__ void __launch_bounds__(512, 2) mega_fwd(Params P) {
;     ...
;         PH(10) { PHASE_BEGIN
;           pg8::BranchOrder S{P5, WBR, LDP, 1024, MP / 256, 8, G, c, 16, 4}; pg8::EpiG2 E{GT, (u32x4*)(ws + WS_XH) + (size_t)c * 16 * 512, HB, PART2, 4};
;           pg8::gemm_phase(lds, LDP, 1024, S, E); }
;         GSYNC();
.LBB0_1297:
	s_waitcnt vmcnt(0)
	v_readlane_b32 s94, v254, 36
	v_readlane_b32 s96, v254, 38
	v_readlane_b32 s90, v254, 40
	v_readlane_b32 s88, v254, 42
	v_readlane_b32 s92, v254, 44
	v_readlane_b32 s74, v254, 46
	v_readlane_b32 s95, v254, 37
	v_readlane_b32 s97, v254, 39
	v_readlane_b32 s91, v254, 41
	v_readlane_b32 s89, v254, 43
	v_readlane_b32 s93, v254, 45
	v_readlane_b32 s75, v254, 47
	s_movk_i32 s71, 0x1ff
	s_barrier
	s_cmpk_lt_u32 s2, 0x60
	s_cbranch_scc1 .Lw2_skip_g2
	v_writelane_b32 v255, s0, 8
	s_nop 1
	v_writelane_b32 v255, s1, 9
	s_nop 1
	v_writelane_b32 v255, s4, 10
	s_nop 1
	v_writelane_b32 v255, s5, 11
	s_nop 1
	v_writelane_b32 v255, s14, 12
	s_nop 1
	v_writelane_b32 v255, s15, 13
	s_nop 1
	v_writelane_b32 v255, s16, 14
	s_nop 1
	v_writelane_b32 v255, s17, 15
	s_nop 1
	v_writelane_b32 v255, s18, 16
	s_nop 1
	v_writelane_b32 v255, s19, 17
	s_nop 1
	v_writelane_b32 v255, s24, 18
	s_nop 1
	v_writelane_b32 v255, s25, 19
	s_nop 1
	v_writelane_b32 v255, s28, 20
	s_nop 1
	v_writelane_b32 v255, s29, 21
	s_nop 1
	v_writelane_b32 v255, s30, 22
	s_nop 1
	v_writelane_b32 v255, s31, 23
	s_nop 1
	v_writelane_b32 v255, s68, 24
	s_nop 1
	v_writelane_b32 v255, s73, 25
	s_nop 1
	s_movk_i32 s73, 0x2000
	s_movk_i32 s100, 0xa0
	s_sub_u32 s101, s2, 0x60
	s_lshl_b32 s101, s101, 3
	s_mov_b32 s4, 0x500
	v_writelane_b32 v255, s4, 50
	s_nop 1
	s_mov_b32 s4, 0x3f0
	v_writelane_b32 v255, s4, 51
	s_nop 1
	s_mov_b32 s4, 0x3
	v_writelane_b32 v255, s4, 53
	s_nop 1
	s_branch .Lw2_entry
.Lw2_ret_g2:
	s_mov_b64 exec, -1
	s_waitcnt vmcnt(0) lgkmcnt(0)
	v_readlane_b32 s0, v255, 8
	v_readlane_b32 s1, v255, 9
	v_readlane_b32 s4, v255, 10
	v_readlane_b32 s5, v255, 11
	v_readlane_b32 s14, v255, 12
	v_readlane_b32 s15, v255, 13
	v_readlane_b32 s16, v255, 14
	v_readlane_b32 s17, v255, 15
	v_readlane_b32 s18, v255, 16
	v_readlane_b32 s19, v255, 17
	v_readlane_b32 s24, v255, 18
	v_readlane_b32 s25, v255, 19
	v_readlane_b32 s28, v255, 20
	v_readlane_b32 s29, v255, 21
	v_readlane_b32 s30, v255, 22
	v_readlane_b32 s31, v255, 23
	v_readlane_b32 s68, v255, 24
	v_readlane_b32 s73, v255, 25
	s_nop 4
.Lw2_skip_g2:
.LBB0_1298:
	s_waitcnt vmcnt(0)
	s_barrier
	s_mov_b64 s[0:1], exec
	v_readlane_b32 s4, v252, 2
	v_readlane_b32 s5, v252, 3
	s_and_b64 s[4:5], s[0:1], s[4:5]
	s_mov_b64 exec, s[4:5]
	s_cbranch_execz .LBB0_1350
	v_readlane_b32 s4, v254, 18
	s_waitcnt vmcnt(0) expcnt(0) lgkmcnt(0)
	s_nop 0
	v_mov_b32_e32 v0, s4
	ds_read_b32 v3, v0
	v_readlane_b32 s4, v254, 19
	s_waitcnt lgkmcnt(0)
	v_cmp_ne_u32_e32 vcc, 0, v3
	v_mov_b32_e32 v0, s4
	ds_read_b32 v2, v0
	s_cbranch_vccnz .LBB0_1314
	s_mov_b32 s18, 1
	s_branch .LBB0_1302

; #define PH(b) if ((PHM >> (b)) & 1)
; #define PHASE_BEGIN unsigned char* ws = opaque_ptr(P.ws); const int z = opaque_zero(); (void)ws; (void)z;
; #define GSYNC() xcd_barrier(xbar)
; __global__ void __launch_bounds__(512, 2) mega_fwd(Params P) {
;     ...
;         PH(11) { PHASE_BEGIN
;           pg8::SplitOrder S{HB, WOUT, D, D, MP / 256, 8, G, c, D / 64, 4, 8}; pg8::EpiMix E{MIX, D, PART, 4};
;           pg8::gemm_phase(lds, D, D, S, E); }
;         GSYNC();
.LBB0_1499:
	s_waitcnt vmcnt(0)
	v_readlane_b32 s90, v254, 40
	v_readlane_b32 s88, v254, 42
	v_readlane_b32 s74, v254, 46
	v_readlane_b32 s91, v254, 41
	v_readlane_b32 s89, v254, 43
	v_readlane_b32 s75, v254, 47
	s_movk_i32 s71, 0x1ff
	s_barrier
	s_cmpk_lt_u32 s2, 0x20
	s_cbranch_scc1 .Lw2_skip_g3
	v_writelane_b32 v255, s0, 8
	s_nop 1
	v_writelane_b32 v255, s1, 9
	s_nop 1
	v_writelane_b32 v255, s4, 10
	s_nop 1
	v_writelane_b32 v255, s5, 11
	s_nop 1
	v_writelane_b32 v255, s14, 12
	s_nop 1
	v_writelane_b32 v255, s15, 13
	s_nop 1
	v_writelane_b32 v255, s16, 14
	s_nop 1
	v_writelane_b32 v255, s17, 15
	s_nop 1
	v_writelane_b32 v255, s18, 16
	s_nop 1
	v_writelane_b32 v255, s19, 17
	s_nop 1
	v_writelane_b32 v255, s24, 18
	s_nop 1
	v_writelane_b32 v255, s25, 19
	s_nop 1
	v_writelane_b32 v255, s28, 20
	s_nop 1
	v_writelane_b32 v255, s29, 21
	s_nop 1
	v_writelane_b32 v255, s30, 22
	s_nop 1
	v_writelane_b32 v255, s31, 23
	s_nop 1
	v_writelane_b32 v255, s68, 24
	s_nop 1
	v_writelane_b32 v255, s73, 25
	s_nop 1
	s_movk_i32 s73, 0x2000
	s_movk_i32 s100, 0xe0
	s_sub_u32 s101, s2, 0x20
	s_lshl_b32 s101, s101, 3
	s_mov_b32 s4, 0x700
	v_writelane_b32 v255, s4, 50
	s_nop 1
	s_mov_b32 s4, 0x8f0
	v_writelane_b32 v255, s4, 51
	s_nop 1
	s_mov_b32 s4, 0x4
	v_writelane_b32 v255, s4, 53
	s_nop 1
	s_branch .Lw2_entry

; #define PH(b) if ((PHM >> (b)) & 1)
; #define PHASE_BEGIN unsigned char* ws = opaque_ptr(P.ws); const int z = opaque_zero(); (void)ws; (void)z;
; __device__ __forceinline__ void xcd_barrier(const XcdBarrier& b) {
;     asm volatile("s_waitcnt vmcnt(0)" ::: "memory");
;     __syncthreads();
;     if (threadIdx.x == 0) {
;         unsigned* bar = b.bar;
;         __builtin_amdgcn_s_waitcnt(0);
;         unsigned nloc = b.st[0], nx = b.st[1];
;         if (nloc == 0u) { xcd_barrier_complete(bar, b.x, nloc, nx); b.st[0] = nloc; b.st[1] = nx; }
; __global__ void __launch_bounds__(512, 2) mega_fwd(Params P) {
;     ...
;         PH(0) { PHASE_BEGIN
;           const float* nw = PIN(I_NORMW) + (size_t)l * 4 * D;
;           phase_norm(P, l == 0 ? 3 : 1, MIX, nw + D, nw + 2 * D, HB, XSB, PART, 4); }
.Lw2_skip_g3:
.LBB0_1500:
	s_waitcnt vmcnt(0)
	s_waitcnt vmcnt(0)
	s_barrier
	s_mov_b64 s[0:1], exec
	v_readlane_b32 s4, v252, 2
	v_readlane_b32 s5, v252, 3
	v_readlane_b32 s92, v254, 44
	s_and_b64 s[4:5], s[0:1], s[4:5]
	v_readlane_b32 s51, v254, 48
	v_readlane_b32 s93, v254, 45
	s_movk_i32 s42, 0x40ff
	v_readlane_b32 s52, v254, 50
	s_mov_b32 s53, 0x8000
	s_mov_b32 s54, 0xa000
	s_mov_b32 s55, 0xc000
	s_mov_b32 s56, 0xe000
	s_mov_b32 s57, 0x16000
	v_readlane_b32 s24, v254, 57
	v_readlane_b32 s25, v254, 58
	s_mov_b64 exec, s[4:5]
	s_cbranch_execz .LBB0_1552
	v_readlane_b32 s4, v254, 18
	s_waitcnt vmcnt(0) expcnt(0) lgkmcnt(0)
	s_nop 0
	v_mov_b32_e32 v0, s4
	ds_read_b32 v3, v0
	v_readlane_b32 s4, v254, 19
	s_waitcnt lgkmcnt(0)
	v_cmp_ne_u32_e32 vcc, 0, v3
	v_mov_b32_e32 v0, s4
	ds_read_b32 v2, v0
	s_cbranch_vccnz .LBB0_1516
	s_mov_b32 s18, 1
	s_branch .LBB0_1504

; __device__ __forceinline__ int opaque_tid() { int t = threadIdx.x; asm volatile("" : "+v"(t)); return t; }
; #define PH(b) if ((PHM >> (b)) & 1)
; #define PHASE_BEGIN unsigned char* ws = opaque_ptr(P.ws); const int z = opaque_zero(); (void)ws; (void)z;
; __global__ void __launch_bounds__(512, 2) mega_fwd(Params P) {
;     ...
;         for (int rep_ = 0; rep_ < ((PROBE_DUP & 32) ? 2 : 1); ++rep_) PH(1) { PHASE_BEGIN
;             const int tid = opaque_tid(), lane = tid & 63, wave = __builtin_amdgcn_readfirstlane(tid >> 6); const int gw = c * 8 + wave, NGW = (G + z) * 8;
;             const float* wf1 = PIN(I_WF1) + (size_t)l * D * 2 * DFF; const float* wf2 = PIN(I_WF2) + (size_t)l * DFF * D;
;             const int n1 = 32 * 44, n2 = 88 * 8;
;             { const int tot4 = (n1 + n2) * 4; const int s0 = (int)((unsigned)(gw * tot4) / (unsigned)NGW), s1 = (int)((unsigned)((gw + 1) * tot4) / (unsigned)NGW);
;             for (int ss = s0; ss < s1; ++ss) {
;                 const int it = ss >> 2, sub = ss & 3;
;                 if (it < n1) transpose_item<1>(wf1, D, 2 * DFF, WF1, it, sub, lane);
;                 else transpose_item<0>(wf2, DFF, D, WF2, it - n1, sub, lane);
;             } }
.LBB0_1573:
	v_writelane_b32 v254, s24, 57
	s_nop 1
	v_writelane_b32 v254, s25, 58
	s_or_b64 exec, exec, s[0:1]
	s_mov_b32 s100, s64
	s_mov_b32 s101, s51
	s_mov_b32 s4, 0x610
	v_writelane_b32 v255, s4, 50
	s_nop 1
	s_mov_b32 s4, 0xff0
	v_writelane_b32 v255, s4, 51
	s_nop 1
	s_mov_b32 s4, 0x0
	v_writelane_b32 v255, s4, 53
	s_nop 1

; __device__ __forceinline__ int opaque_tid() { int t = threadIdx.x; asm volatile("" : "+v"(t)); return t; }
; #define PH(b) if ((PHM >> (b)) & 1)
; #define PHASE_BEGIN unsigned char* ws = opaque_ptr(P.ws); const int z = opaque_zero(); (void)ws; (void)z;
; #define GSYNC() xcd_barrier(xbar)
; __global__ void __launch_bounds__(512, 2) mega_fwd(Params P) {
;     ...
;         for (int rep_ = 0; rep_ < ((PROBE_DUP & 32) ? 2 : 1); ++rep_) PH(1) { PHASE_BEGIN
;             const int tid = opaque_tid(), lane = tid & 63, wave = __builtin_amdgcn_readfirstlane(tid >> 6); const int gw = c * 8 + wave, NGW = (G + z) * 8;
;             const float* wf1 = PIN(I_WF1) + (size_t)l * D * 2 * DFF; const float* wf2 = PIN(I_WF2) + (size_t)l * DFF * D;
;             const int n1 = 32 * 44, n2 = 88 * 8;
;             { const int tot4 = (n1 + n2) * 4; const int s0 = (int)((unsigned)(gw * tot4) / (unsigned)NGW), s1 = (int)((unsigned)((gw + 1) * tot4) / (unsigned)NGW);
;             for (int ss = s0; ss < s1; ++ss) {
;                 const int it = ss >> 2, sub = ss & 3;
;                 if (it < n1) transpose_item<1>(wf1, D, 2 * DFF, WF1, it, sub, lane);
;                 else transpose_item<0>(wf2, DFF, D, WF2, it - n1, sub, lane);
;             } }
;         }
;         GSYNC();
.LBB0_1584:
	v_readlane_b32 s0, v255, 53
	s_nop 3
	s_cmp_eq_u32 s0, 0
	s_cbranch_scc1 .Lw2_norm
	s_cmp_eq_u32 s0, 1
	s_cbranch_scc1 .Lw2_ret_g4
	s_cmp_eq_u32 s0, 2
	s_cbranch_scc1 .Lw2_ret_glu
	s_cmp_eq_u32 s0, 3
	s_cbranch_scc1 .Lw2_ret_g2
	s_branch .Lw2_ret_g3

; #define PH(b) if ((PHM >> (b)) & 1)
; #define PHASE_BEGIN unsigned char* ws = opaque_ptr(P.ws); const int z = opaque_zero(); (void)ws; (void)z;
; #define GSYNC() xcd_barrier(xbar)
; __global__ void __launch_bounds__(512, 2) mega_fwd(Params P) {
;     ...
;         PH(11) { PHASE_BEGIN
;           pg8::SplitOrder S{HID, WF2, DFF, DFF, MP / 256, 8, G, c, DFF / 64, 11, 8}; pg8::EpiMix E{FFO, D, PART, 11};
;     ...
;           pg8::gemm_phase(lds, DFF, DFF, S, E);
;     ...
;           pg8::gemm_phase(lds, DFF, DFF, S, E); }
;         GSYNC();
.LBB0_1655:
	s_waitcnt vmcnt(0)
	v_readlane_b32 s51, v254, 48
	s_movk_i32 s42, 0x40ff
	v_readlane_b32 s52, v254, 50
	s_mov_b32 s53, 0x8000
	s_mov_b32 s54, 0xa000
	s_mov_b32 s55, 0xc000
	s_mov_b32 s56, 0xe000
	s_mov_b32 s57, 0x16000
	v_readlane_b32 s24, v254, 57
	s_barrier
	v_readlane_b32 s25, v254, 58
	s_cmpk_lt_u32 s2, 0x2c
	s_cbranch_scc1 .Lw2_skip_g4
	v_writelane_b32 v255, s0, 8
	s_nop 1
	v_writelane_b32 v255, s1, 9
	s_nop 1
	v_writelane_b32 v255, s4, 10
	s_nop 1
	v_writelane_b32 v255, s5, 11
	s_nop 1
	v_writelane_b32 v255, s14, 12
	s_nop 1
	v_writelane_b32 v255, s15, 13
	s_nop 1
	v_writelane_b32 v255, s16, 14
	s_nop 1
	v_writelane_b32 v255, s17, 15
	s_nop 1
	v_writelane_b32 v255, s18, 16
	s_nop 1
	v_writelane_b32 v255, s19, 17
	s_nop 1
	v_writelane_b32 v255, s24, 18
	s_nop 1
	v_writelane_b32 v255, s25, 19
	s_nop 1
	v_writelane_b32 v255, s28, 20
	s_nop 1
	v_writelane_b32 v255, s29, 21
	s_nop 1
	v_writelane_b32 v255, s30, 22
	s_nop 1
	v_writelane_b32 v255, s31, 23
	s_nop 1
	v_writelane_b32 v255, s68, 24
	s_nop 1
	v_writelane_b32 v255, s73, 25
	s_nop 1
	s_movk_i32 s73, 0x2000
	s_movk_i32 s100, 0xd4
	s_sub_u32 s101, s2, 0x2c
	s_lshl_b32 s101, s101, 3
	s_mov_b32 s4, 0xb00
	v_writelane_b32 v255, s4, 50
	s_nop 1
	s_mov_b32 s4, 0x1600
	v_writelane_b32 v255, s4, 51
	s_nop 1
	s_mov_b32 s4, 0x1
	v_writelane_b32 v255, s4, 53
	s_nop 1
	s_branch .Lw2_entry
